# Hyena L=2048 block-Toeplitz MFMA loop software-pipelined by hand (LDS fragment reads 3 iterations ahead of their MFMAs)
# speedup vs baseline: 1.0509x; 1.0015x over previous
.LBB0_973:
	s_or_b64 exec, exec, s[16:17]
	s_ashr_i32 s21, s20, 3
	s_and_b32 s18, s21, -8
	s_max_i32 s22, s18, 0
	s_or_b32 s19, s21, 7
	s_lshl_b64 s[16:17], s[12:13], 11
	s_sub_i32 s20, s22, 63
	s_min_i32 s19, s19, 63
	v_mov_b32_e32 v9, 0
	s_cmp_gt_i32 s20, s19
	v_mov_b32_e32 v8, v9
	v_mov_b32_e32 v7, v9
	v_mov_b32_e32 v6, v9
	v_mov_b32_e32 v5, v9
	v_mov_b32_e32 v4, v9
	v_mov_b32_e32 v3, v9
	v_mov_b32_e32 v2, v9
	s_waitcnt lgkmcnt(0)
	s_barrier
	s_cbranch_scc1 .LBB0_976
	s_lshl_b32 s21, s21, 6
	s_sub_i32 s20, s22, 64
	s_lshl_b32 s22, s22, 6
	s_and_b32 s21, s21, 0xfffffe00
	s_sub_i32 s21, s21, s22
	v_mov_b32_e32 v6, 0
	v_subrev_u32_e32 v25, s22, v31
	v_add_u32_e32 v43, s21, v32
	v_mov_b32_e32 v7, v6
	v_mov_b32_e32 v8, v6
	v_mov_b32_e32 v9, v6
	v_mov_b32_e32 v2, v6
	v_mov_b32_e32 v3, v6
	v_mov_b32_e32 v4, v6
	v_mov_b32_e32 v5, v6
	s_sub_i32 s20, s19, s20
	s_add_i32 s21, s20, -1
	s_lshl_b32 s21, s21, 6
	v_subrev_u32_e32 v62, s21, v25
	v_subrev_u32_e32 v63, s21, v43
	ds_read_b128 v[64:67], v25 offset:32
	ds_read_b128 v[68:71], v43
	ds_read_b128 v[72:75], v25
	v_subrev_u32_e32 v25, 64, v25
	v_subrev_u32_e32 v43, 64, v43
	v_max_i32_e32 v25, v25, v62
	v_max_i32_e32 v43, v43, v63
	ds_read_b128 v[76:79], v25 offset:32
	ds_read_b128 v[80:83], v43
	ds_read_b128 v[84:87], v25
	v_subrev_u32_e32 v25, 64, v25
	v_subrev_u32_e32 v43, 64, v43
	v_max_i32_e32 v25, v25, v62
	v_max_i32_e32 v43, v43, v63
	ds_read_b128 v[88:91], v25 offset:32
	ds_read_b128 v[92:95], v43
	ds_read_b128 v[96:99], v25
	v_subrev_u32_e32 v25, 64, v25
	v_subrev_u32_e32 v43, 64, v43
	v_max_i32_e32 v25, v25, v62
	v_max_i32_e32 v43, v43, v63
.Lhy_loop:
	ds_read_b128 v[100:103], v25 offset:32
	ds_read_b128 v[104:107], v43
	ds_read_b128 v[108:111], v25
	v_subrev_u32_e32 v25, 64, v25
	v_subrev_u32_e32 v43, 64, v43
	v_max_i32_e32 v25, v25, v62
	v_max_i32_e32 v43, v43, v63
	s_waitcnt lgkmcnt(9)
	v_mfma_f32_16x16x32_bf16 v[6:9], v[64:67], v[68:71], v[6:9]
	v_mfma_f32_16x16x32_bf16 v[2:5], v[72:75], v[68:71], v[2:5]
	s_add_i32 s20, s20, -1
	s_cmp_eq_u32 s20, 0
	s_cbranch_scc1 .Lhy_done
	ds_read_b128 v[64:67], v25 offset:32
	ds_read_b128 v[68:71], v43
	ds_read_b128 v[72:75], v25
	v_subrev_u32_e32 v25, 64, v25
	v_subrev_u32_e32 v43, 64, v43
	v_max_i32_e32 v25, v25, v62
	v_max_i32_e32 v43, v43, v63
	s_waitcnt lgkmcnt(9)
	v_mfma_f32_16x16x32_bf16 v[6:9], v[76:79], v[80:83], v[6:9]
	v_mfma_f32_16x16x32_bf16 v[2:5], v[84:87], v[80:83], v[2:5]
	s_add_i32 s20, s20, -1
	s_cmp_eq_u32 s20, 0
	s_cbranch_scc1 .Lhy_done
	ds_read_b128 v[76:79], v25 offset:32
	ds_read_b128 v[80:83], v43
	ds_read_b128 v[84:87], v25
	v_subrev_u32_e32 v25, 64, v25
	v_subrev_u32_e32 v43, 64, v43
	v_max_i32_e32 v25, v25, v62
	v_max_i32_e32 v43, v43, v63
	s_waitcnt lgkmcnt(9)
	v_mfma_f32_16x16x32_bf16 v[6:9], v[88:91], v[92:95], v[6:9]
	v_mfma_f32_16x16x32_bf16 v[2:5], v[96:99], v[92:95], v[2:5]
	s_add_i32 s20, s20, -1
	s_cmp_eq_u32 s20, 0
	s_cbranch_scc1 .Lhy_done
	ds_read_b128 v[88:91], v25 offset:32
	ds_read_b128 v[92:95], v43
	ds_read_b128 v[96:99], v25
	v_subrev_u32_e32 v25, 64, v25
	v_subrev_u32_e32 v43, 64, v43
	v_max_i32_e32 v25, v25, v62
	v_max_i32_e32 v43, v43, v63
	s_waitcnt lgkmcnt(9)
	v_mfma_f32_16x16x32_bf16 v[6:9], v[100:103], v[104:107], v[6:9]
	v_mfma_f32_16x16x32_bf16 v[2:5], v[108:111], v[104:107], v[2:5]
	s_add_i32 s20, s20, -1
	s_cmp_eq_u32 s20, 0
	s_cbranch_scc1 .Lhy_done
	s_branch .Lhy_loop
.Lhy_done:
	s_waitcnt lgkmcnt(0)
